# attention: static s_setprio 1 for waves 4-7 during P5 (reset at phase end)
# baseline (speedup 1.0000x reference)
; #define VMW() asm volatile("s_waitcnt vmcnt(0)" ::: "memory")
; #define SLOAD_H(Kp, Vp, k0) do { S.st_v0 = load8(ROW(Vp, k0, sr)); S.st_v1 = load8(ROW(Vp, k0, 32 + sr));              \
;                          S.st_k0 = load8(ROW(Kp, k0, sr)); S.st_k1 = load8(ROW(Kp, k0, 32 + sr)); } while (0)
; #define SWRITE_HK(bf) do { *(bf16x8*)(K_lds + (bf) * SHM_K + kws) = S.st_k0; *(bf16x8*)(K_lds + (bf) * SHM_K + kws + 32 * 256) = S.st_k1; } while (0)
; __device__ __forceinline__ void attn_prime(const BlockRef& cur, char* lds, Seam& S) {
;     const int tid = threadIdx.x, wid = __builtin_amdgcn_readfirstlane(tid >> 6), lane = tid & 63, r32 = lane & 31, hi = lane >> 5;
;     const int sr = tid >> 4, sc = (tid & 15) * 8, kws = KSWZ(sr, sc * 2); char* K_lds = lds + 2 * SHM_V;
; #pragma unroll
;     for (int d0 = 0; d0 < 8; ++d0) S.qr[d0] = load8(cur.Q + (size_t)(wid * QBLK + r32) * LD + d0 * 16 + hi * 8);
;     SLOAD_H(cur.K, cur.V, 0); VMW(); SWRITE_HK(0);
;     __syncthreads();
; }
; __device__ __forceinline__ void attn_phase(char* lds, const bf16* Q, const bf16* K, const bf16* V, bf16* O, const unsigned long long* MW, int first, int stride) {
;     constexpr int total = (DUP_PHASE == 5) ? 1024 : 512;
;     int L = first; if (L >= total) return;
;     Item it = decode(L); int pass = 0;
;     BlockRef cur = mkref(it, 0, Q, K, V, O, MW);
;     Seam S;
;     attn_prime(cur, lds, S);
.LBB0_1289:
	s_cmp_lt_i32 s54, 6
	s_cselect_b64 s[8:9], -1, 0
	s_and_b64 s[0:1], s[8:9], s[0:1]
	s_andn2_b64 vcc, exec, s[0:1]
	s_cbranch_vccnz .LBB0_1447
	s_cmpk_gt_i32 s2, 0x1ff
	s_cbranch_scc1 .LBB0_1447
	v_readfirstlane_b32 s98, v0
	s_lshr_b32 s98, s98, 8
	s_cmp_eq_u32 s98, 0
	s_cbranch_scc1 .Lp5_noprio
	s_setprio 1
.Lp5_noprio:
	s_add_u32 s3, s52, 0xc000000
	s_addc_u32 s15, s53, 0
	s_add_u32 s33, s52, 0x10000000
	s_addc_u32 s35, s53, 0
	s_add_u32 s56, s52, 0x14000000
	s_addc_u32 s57, s53, 0
	s_add_u32 s58, s52, 0x2e00000
	s_addc_u32 s59, s53, 0
	s_lshl_b32 s4, s2, 3
	s_bfe_u32 s1, s2, 0x30003
	s_and_b32 s4, s4, 56
	s_lshl_b32 s5, s4, 9
	s_lshl_b32 s38, s1, 8
	s_bfe_u32 s0, s2, 0x30006
	s_xor_b32 s73, s1, 15
	s_or_b32 s1, s5, s38
	s_or_b32 s72, s4, s0
	s_lshl_b32 s5, s1, 11
	s_add_u32 s6, s3, s5
	s_addc_u32 s7, s15, 0
	s_lshl_b32 s0, s0, 8
	s_add_u32 s10, s6, s0
	s_addc_u32 s11, s7, 0
	s_add_u32 s5, s30, s5
	s_addc_u32 s6, s31, 0
	s_add_u32 s66, s5, s0
	s_addc_u32 s67, s6, 0
	s_lshl_b32 s4, s4, 20
	s_add_u32 s5, s33, s4
	s_addc_u32 s7, s35, 0
	s_add_u32 s6, s5, s0
	s_addc_u32 s7, s7, 0
	s_add_u32 s4, s56, s4
	s_addc_u32 s5, s57, 0
	s_add_u32 s70, s4, s0
	s_addc_u32 s71, s5, 0
	s_lshl_b32 s0, s1, 9
	s_add_u32 s68, s58, s0
	v_readfirstlane_b32 s0, v0
	s_addc_u32 s69, s59, 0
	s_lshr_b32 s0, s0, 1
	s_waitcnt vmcnt(0)
	v_and_b32_e32 v30, 31, v0
	s_and_b32 s0, s0, 0x7fffffe0
	v_or_b32_e32 v166, s0, v30
	v_mov_b32_e32 v167, 0
	v_lshlrev_b64 v[2:3], 11, v[166:167]
	v_lshrrev_b32_e32 v1, 1, v0
	v_lshl_add_u64 v[2:3], s[10:11], 0, v[2:3]
	v_and_b32_e32 v166, 16, v1
	v_lshrrev_b32_e32 v1, 4, v0
	v_lshlrev_b32_e32 v13, 3, v0
	v_lshl_add_u64 v[10:11], v[2:3], 0, v[166:167]
	v_and_b32_e32 v12, 0x78, v13
	v_lshlrev_b32_e32 v166, 11, v1
	v_lshlrev_b32_e32 v14, 1, v12
	v_mov_b32_e32 v15, v167
	v_lshl_add_u64 v[2:3], s[6:7], 0, v[166:167]
	s_mov_b32 s0, 0x10000
	v_lshl_add_u64 v[16:17], v[2:3], 0, v[14:15]
	v_add_co_u32_e32 v18, vcc, s0, v16
	v_bfe_u32 v21, v0, 4, 2
	s_nop 0
	v_addc_co_u32_e32 v19, vcc, 0, v17, vcc
	global_load_dwordx4 v[2:5], v[16:17], off
	global_load_dwordx4 v[6:9], v[18:19], off
	global_load_dwordx4 v[126:129], v[10:11], off
	global_load_dwordx4 v[122:125], v[10:11], off offset:32
	global_load_dwordx4 v[118:121], v[10:11], off offset:64
	global_load_dwordx4 v[114:117], v[10:11], off offset:96
	global_load_dwordx4 v[110:113], v[10:11], off offset:128
	global_load_dwordx4 v[106:109], v[10:11], off offset:160
	global_load_dwordx4 v[102:105], v[10:11], off offset:192
	global_load_dwordx4 v[98:101], v[10:11], off offset:224
	v_lshl_add_u64 v[10:11], s[70:71], 0, v[166:167]
	v_lshrrev_b32_e32 v18, 3, v0
	v_lshl_add_u64 v[10:11], v[10:11], 0, v[14:15]
	v_lshrrev_b32_e32 v19, 5, v0
	v_and_b32_e32 v25, 8, v18
	v_add_co_u32_e32 v18, vcc, s0, v10
	v_and_or_b32 v21, v19, 4, v21
	s_nop 0
	v_addc_co_u32_e32 v19, vcc, 0, v11, vcc
	global_load_dwordx4 v[130:133], v[10:11], off
	global_load_dwordx4 v[134:137], v[18:19], off
	s_movk_i32 s1, 0x70
	v_lshlrev_b32_e32 v24, 8, v1
	v_lshlrev_b32_e32 v16, 10, v1
	v_or_b32_e32 v27, 32, v1
	v_and_or_b32 v1, v1, 16, v25
	v_bitop3_b32 v15, v14, v0, s1 bitop3:0x78
	v_lshrrev_b32_e32 v20, 5, v162
	v_bfe_u32 v26, v13, 5, 2
	v_lshrrev_b32_e32 v1, 1, v1
	v_add3_u32 v15, 0, v24, v15
	v_lshlrev_b32_e32 v22, 4, v0
	v_and_or_b32 v11, v27, 48, v25
	v_or_b32_e32 v1, v1, v26
	s_waitcnt vmcnt(0)
	v_and_b32_e32 v17, 0x70, v0
	v_lshlrev_b32_e32 v10, 6, v21
	v_and_b32_e32 v18, 48, v14
	v_lshrrev_b32_e32 v11, 1, v11
	v_lshlrev_b32_e32 v1, 9, v1
	v_lshlrev_b32_e32 v23, 1, v0
	v_bitop3_b32 v14, v14, v24, v17 bitop3:0xde
	v_or_b32_e32 v11, v11, v26
	v_or3_b32 v17, v1, v10, v18
	v_and_b32_e32 v1, 0x118, v13
	v_and_b32_e32 v13, 1, v0
	v_and_b32_e32 v28, 0xc0, v22
	v_and_b32_e32 v23, 32, v23
	v_lshlrev_b32_e32 v11, 9, v11
	s_cmp_lg_u32 0, -1
	v_cmp_eq_u32_e64 s[4:5], 0, v13
	v_and_b32_e32 v13, 15, v0
	v_or3_b32 v10, v11, v10, v18
	v_or3_b32 v1, v23, v28, v1
	s_cselect_b32 s0, 0, 0
	v_lshlrev_b32_e32 v170, 4, v13
	v_lshlrev_b32_e32 v13, 7, v0
	s_mov_b32 s13, 0
	v_add_u32_e32 v1, s0, v1
	v_lshlrev_b32_e32 v163, 2, v20
	v_cmp_gt_u32_e64 s[0:1], 32, v162
	v_lshlrev_b32_e32 v168, 13, v20
	s_waitcnt vmcnt(11)
	ds_write_b128 v15, v[2:5] offset:32768
	s_waitcnt vmcnt(10)
	ds_write_b128 v15, v[6:9] offset:40960
	v_lshlrev_b32_e32 v2, 4, v20
	v_and_b32_e32 v4, 0x70, v22
	v_or_b32_e32 v6, 32, v2
	v_xad_u32 v7, v6, v4, 0
	v_or_b32_e32 v6, 64, v2
	v_xad_u32 v5, v2, v4, 0
	v_xad_u32 v9, v6, v4, 0
	v_or_b32_e32 v2, 0x60, v2
	v_lshlrev_b32_e32 v6, 10, v27
	v_lshlrev_b32_e32 v3, 8, v30
	v_xad_u32 v11, v2, v4, 0
	v_or_b32_e32 v2, 0x10000, v16
	v_or_b32_e32 v4, 0x18000, v16
	v_lshlrev_b32_e32 v8, 3, v20
	v_lshlrev_b32_e32 v178, 1, v6
	v_mbcnt_lo_u32_b32 v6, -1, 0
	v_mov_b32_e32 v169, v167
	v_lshl_or_b32 v254, v30, 9, 16
	v_mov_b32_e32 v171, v167
	v_and_b32_e32 v252, 0xf800, v13
	v_mov_b32_e32 v253, v167
	s_mov_b32 s74, 0xff800000
	s_mov_b32 s75, 0x41000000
	s_mov_b32 s14, 0x3e0293ee
	s_mov_b32 s76, 0x40000
	s_mov_b32 s77, 0x50000
	s_mov_b64 s[16:17], 0x40000
	s_mov_b64 s[100:101], 0x50000
	v_lshlrev_b32_e32 v164, 1, v16
	v_lshlrev_b32_e32 v176, 1, v12
	v_lshlrev_b32_e32 v180, 1, v8
	v_mbcnt_hi_u32_b32 v196, -1, v6
	v_lshlrev_b32_e32 v166, 1, v30
	v_add_u32_e32 v197, 0, v17
	v_add_u32_e32 v198, 0, v10
	v_lshlrev_b32_e32 v182, 1, v2
	v_lshlrev_b32_e32 v184, 1, v4
	v_add_u32_e32 v199, v5, v3
	v_add_u32_e32 v200, v7, v3
	v_add_u32_e32 v201, v9, v3
	v_add_u32_e32 v202, v11, v3
	v_mov_b32_e32 v203, 0xf149f2ca
	v_add_u32_e32 v204, 0, v14
	s_mov_b32 s79, 0
	s_mov_b32 s78, s2
	s_waitcnt lgkmcnt(0)
	s_barrier
	s_branch .LBB0_1293

; __device__ __forceinline__ unsigned xb_ld(unsigned* p)              { return __hip_atomic_load(p, __ATOMIC_RELAXED, __HIP_MEMORY_SCOPE_AGENT); }
; __device__ __forceinline__ void xcd_barrier_complete(unsigned* bar, unsigned x, unsigned& nloc, unsigned& nx) {
;     const unsigned G = gridDim.x * gridDim.y * gridDim.z;
;     unsigned sum, cnt, mine, sp = 0u;
;     for (;;) {
;         sum = 0u; cnt = 0u; mine = 0u;
; #pragma unroll
;         for (unsigned j = 0; j < 16; ++j) { const unsigned c = xb_ld(&bar[XB_XCNT(j)]); sum += c; cnt += (c > 0u) ? 1u : 0u; mine = (j == x) ? c : mine; }
; __device__ __forceinline__ void xcd_barrier(const XcdBarrier& b) {
;     asm volatile("s_waitcnt vmcnt(0)" ::: "memory");
;     __syncthreads();
;     if (threadIdx.x == 0) {
;         unsigned* bar = b.bar;
;         __builtin_amdgcn_s_waitcnt(0);
;         unsigned nloc = b.st[0], nx = b.st[1];
;         if (nloc == 0u) { xcd_barrier_complete(bar, b.x, nloc, nx); b.st[0] = nloc; b.st[1] = nx; }
.LBB0_1447:
	s_setprio 0
	s_cmp_gt_i32 s55, 6
	s_cselect_b64 s[0:1], -1, 0
	s_and_b64 s[4:5], s[8:9], s[0:1]
	s_andn2_b64 vcc, exec, s[4:5]
	s_cbranch_vccnz .LBB0_1497
	s_waitcnt vmcnt(0)
	v_cmp_eq_u32_e32 vcc, 0, v0
	s_waitcnt vmcnt(0)
	s_barrier
	s_and_saveexec_b64 s[4:5], vcc
	s_cbranch_execz .LBB0_1496
	v_mov_b32_e32 v1, s88
	s_waitcnt vmcnt(0) expcnt(0) lgkmcnt(0)
	ds_read_b32 v3, v1
	ds_read_b32 v1, v1 offset:4
	s_waitcnt lgkmcnt(1)
	v_cmp_ne_u32_e32 vcc, 0, v3
	s_cbranch_vccnz .LBB0_1464
	s_load_dwordx2 s[10:11], s[90:91], 0x4
	s_add_u32 s6, s52, 0x4200
	s_addc_u32 s7, s53, 0
	s_add_u32 s8, s52, 0x4400
	s_addc_u32 s9, s53, 0
	s_waitcnt lgkmcnt(0)
	s_mul_i32 s3, s10, s34
	s_add_u32 s10, s52, 0x4500
	s_mul_i32 s3, s3, s11
	s_addc_u32 s11, s53, 0
	s_add_u32 s12, s52, 0x4600
	s_addc_u32 s13, s53, 0
	s_add_u32 s14, s52, 0x4700
	s_addc_u32 s15, s53, 0
	s_add_u32 s16, s52, 0x4800
	s_addc_u32 s17, s53, 0
	s_add_u32 s22, s52, 0x4900
	s_addc_u32 s23, s53, 0
	s_add_u32 s24, s52, 0x4a00
	s_addc_u32 s25, s53, 0
	s_add_u32 s36, s52, 0x4b00
	s_addc_u32 s37, s53, 0
	s_add_u32 s38, s52, 0x4c00
	s_addc_u32 s39, s53, 0
	s_add_u32 s40, s52, 0x4d00
	s_addc_u32 s41, s53, 0
	s_add_u32 s42, s52, 0x4e00
	s_addc_u32 s43, s53, 0
	s_add_u32 s44, s52, 0x4f00
	s_addc_u32 s45, s53, 0
	s_add_u32 s46, s52, 0x5000
	s_addc_u32 s47, s53, 0
	s_add_u32 s48, s52, 0x5100
	s_addc_u32 s49, s53, 0
	s_add_u32 s50, s52, 0x5200
	s_addc_u32 s51, s53, 0
	s_add_u32 s60, s52, 0x5300
	s_addc_u32 s61, s53, 0
	s_mov_b32 s33, 1
	v_mov_b32_e32 v17, 0
	s_branch .LBB0_1452
